# xattn PV output staged in d_out (no aliasing with mixer buffer) so out-proj to xattn-q seam uses the clique barrier
# speedup vs baseline: 1.0319x; 1.0020x over previous
; __device__ __forceinline__ unsigned xb_ld(unsigned* p)              { return __hip_atomic_load(p, __ATOMIC_RELAXED, __HIP_MEMORY_SCOPE_AGENT); }
; __device__ __forceinline__ unsigned xb_add(unsigned* p, unsigned v) { return __hip_atomic_fetch_add(p, v, __ATOMIC_RELAXED, __HIP_MEMORY_SCOPE_AGENT); }
; #define XB_SPIN(cond, bar) do { unsigned _sp = 0; while (cond) { __builtin_amdgcn_s_sleep(1); \
;     if ((++_sp & 255u) == 0u) { if (xb_ld(&(bar)[XB_TMO])) break; if (_sp > XB_SPIN_CAP) { atomicAdd(&(bar)[XB_TMO], 1u); break; } } } } while (0)
; #define GSYNC() do { XcdBarrier xb_; xb_.bar = (unsigned*)(KARGS()->ws + WS_CTL) + 1024; xb_.x = xb_xcc_id(); xb_.st = (volatile LAS unsigned*)(lds + LDS_XB); xcd_barrier(xb_); } while (0)
; __device__ __forceinline__ void xcd_barrier(const XcdBarrier& b) {
;     asm volatile("s_waitcnt vmcnt(0)" ::: "memory");
;     __syncthreads();
;     if (threadIdx.x == 0) {
;         unsigned* bar = b.bar;
;         __builtin_amdgcn_s_waitcnt(0);
;         unsigned nloc = b.st[0], nx = b.st[1];
;         if (nloc == 0u) { xcd_barrier_complete(bar, b.x, nloc, nx); b.st[0] = nloc; b.st[1] = nx; }
;         const unsigned old = xb_add(&bar[XB_XSUB(b.x)], 1u);
;         const unsigned gen = old / nloc;
;         if (old + 1u == (gen + 1u) * nloc) {
;             __builtin_amdgcn_fence(__ATOMIC_RELEASE, "agent");
;             asm volatile("s_waitcnt vmcnt(0)" ::: "memory");
;             const unsigned og = xb_add(&bar[XB_TOP], 1u);
;             const unsigned tg = og / nx;
;             if (og + 1u == (tg + 1u) * nx) xb_add(&bar[XB_TOPGEN], 1u);
;             else XB_SPIN(xb_ld(&bar[XB_TOPGEN]) == tg, bar);
;             __builtin_amdgcn_fence(__ATOMIC_ACQUIRE, "agent");
;             xb_add(&bar[XB_XGEN(b.x)], 1u);
;             asm volatile("s_waitcnt vmcnt(0)" ::: "memory");
;         } else {
;             XB_SPIN(xb_ld(&bar[XB_XGEN(b.x)]) == gen, bar);
;             __builtin_amdgcn_fence(__ATOMIC_ACQUIRE, "agent");
;             asm volatile("s_waitcnt vmcnt(0)" ::: "memory");
;         }
;     }
;     __syncthreads();
; }
; __global__ void __launch_bounds__(512, 2) fwd_kernel(Args a) {
;     ...
;         GSYNC();
.LBB0_1525:
	s_mov_b64 s[8:9], s[0:1]
	s_getreg_b32 s2, hwreg(HW_REG_XCC_ID, 0, 4)
	s_waitcnt vmcnt(0)
	v_readlane_b32 s6, v255, 0
	v_readlane_b32 s7, v255, 1
	s_waitcnt lgkmcnt(0)
	s_barrier
	v_readlane_b32 s4, v255, 40
	s_nop 1
	s_cmp_eq_u32 s4, 0
	s_cbranch_scc1 .Lfs2
	s_and_saveexec_b64 s[4:5], s[6:7]
	s_cbranch_execz .Lfe2
	s_load_dwordx2 s[8:9], s[0:1], 0x128
	v_readlane_b32 s10, v255, 41
	v_readlane_b32 s11, v255, 8
	s_nop 1
	s_and_b32 s11, s11, 63
	s_lshl_b32 s11, s11, 6
	s_addk_i32 s11, 0x6200
	v_mov_b32_e32 v2, 0
	v_mov_b32_e32 v3, 1
	s_add_i32 s10, s10, 1
	s_lshl_b32 s10, s10, 2
	s_waitcnt lgkmcnt(0)
	s_add_u32 s8, s8, s11
	s_addc_u32 s9, s9, 0
	global_atomic_add v2, v3, s[8:9]

; #define PG8_STAGE(bufoff, gbase, voff) do { _Pragma("unroll") for (int _i = 0; _i < 2; ++_i) \
;         __builtin_amdgcn_global_load_lds((const unsigned*)((const char*)(gbase) + (voff)[_i]), (LAS unsigned*)(lds + (bufoff) + ldsw + _i * 8192), 16, 0, 0); } while (0)
; #define PG8_LDA(dst, b, h) do { _Pragma("unroll") for (int m = 0; m < 4; ++m) _Pragma("unroll") for (int k = 0; k < 2; ++k) dst[m][k] = *(const LAS bf16x8*)(lds + PG8_SA(b, h) + aoff + m * 2048 + k * 1024); } while (0)
; #define PG8_LDB(dst, b, h) do { _Pragma("unroll") for (int n = 0; n < 2; ++n) _Pragma("unroll") for (int k = 0; k < 2; ++k) dst[n][k] = *(const LAS bf16x8*)(lds + PG8_SB(b, h) + boff + n * 2048 + k * 1024); } while (0)
; #define PG8_WAIT_V(n) asm volatile("s_waitcnt vmcnt(" #n ")" ::: "memory")
; #define PG8_BAR __builtin_amdgcn_s_barrier()
; template <class Epi, class Sched, bool ALIGN_EPI>
; __device__ __forceinline__ void gemm_phase(LAS unsigned char* lds, const bf16_t* Ab, const bf16_t* Bb, int lda, int ldb, int K, const Sched& S, Epi& E) {
;     ...
;     for (;;) {
;         const bool has_next = S.next(ui + 1, nxt); nxt.ui = ui + 1;
;         const char* nA = has_next ? (const char*)(Ab + nxt.a_off) : cA; const char* nB = has_next ? (const char*)(Bb + nxt.b_off) : cB;
;         for (int t = 0; t < nt; t += 2) {
;             const bool last = (t == nt - 2);
;             const char* a1 = cA + (unsigned)(t + 1) * kstep;
;             const char* a2 = last ? nA : cA + (unsigned)(t + 2) * kstep; const char* b2 = last ? nB : cB + (unsigned)(t + 2) * kstep;
;             const char* a3 = a2 + kstep; const char* b3 = b2 + kstep;
;             PG8_LDB(B0, 0, 0); PG8_LDB(B1, 0, 1); PG8_SCHED; PG8_LDA(At, 0, 0); PG8_STAGE(PG8_SA(1, 1), a1 + hstepA, voffA);
;             PG8_WAIT_V(8); PG8_WAIT_L(0); PG8_BAR; PG8_MMA(0, 0, At, B0); PG8_MMA(0, 1, At, B1); PG8_BAR; PG8_SCHED;
;             PG8_LDA(At, 0, 1); PG8_STAGE(PG8_SB(0, 0), b2, voffB); PG8_STAGE(PG8_SB(0, 1), b2 + hstepB, voffB); PG8_STAGE(PG8_SA(0, 0), a2, voffA);
; __global__ void __launch_bounds__(512, 2) fwd_kernel(Args a) {
;     ...
;         for (int rep = 0; rep < (PROBE == 3 ? 2 : 1); ++rep)
;         { PH XaSched S{G, bid, 4u * 65536u, 65536u}; EpiPV E{(bf16_t*)(ar + AR_OX)};
;           gemm_phase<EpiPV, XaSched, false>(lds, (const bf16_t*)(ar + AR_P), (const bf16_t*)(ws + WS_VXT) + (size_t)l * 1024 * 1024, D, 256, 256, S, E); }
.LBB0_1811:
	s_load_dwordx2 s[6:7], s[0:1], 0x120
	s_waitcnt lgkmcnt(0)
	s_lshl_b32 s10, s10, 5
	s_and_b32 s13, s10, 0x60
	s_add_i32 m0, s31, 0x18000
	v_lshl_add_u64 v[14:15], v[14:15], 0, s[26:27]
	s_lshl_b32 s45, s11, 6
	s_lshl_b32 s12, s11, 13
	s_lshl_b32 s46, s13, 7
	s_waitcnt vmcnt(2)
	s_barrier
	global_load_lds_dwordx4 v[14:15], off
	v_lshl_add_u64 v[12:13], v[12:13], 0, s[26:27]
	s_add_i32 m0, s31, 0x1a000
	s_add_i32 s47, s31, 0x8000
	s_add_i32 s56, s31, 0xa000
	global_load_lds_dwordx4 v[12:13], off
	v_lshl_add_u64 v[10:11], v[10:11], 0, s[26:27]
	s_mov_b32 m0, s47
	s_add_u32 s10, s52, 0x10080
	global_load_lds_dwordx4 v[10:11], off
	v_lshl_add_u64 v[8:9], v[8:9], 0, s[26:27]
	s_mov_b32 m0, s56
	s_addc_u32 s11, s53, 0
	global_load_lds_dwordx4 v[8:9], off
	s_add_i32 m0, s31, 0x1c000
	v_lshl_add_u64 v[8:9], s[10:11], 0, v[2:3]
	global_load_lds_dwordx4 v[8:9], off
	v_lshl_add_u64 v[8:9], s[10:11], 0, v[4:5]
	s_add_i32 m0, s31, 0x1e000
	v_lshlrev_b32_e32 v7, 6, v16
	global_load_lds_dwordx4 v[8:9], off
	v_and_b32_e32 v18, 0x3c0, v7
	v_lshlrev_b32_e32 v7, 2, v16
	v_and_b32_e32 v17, 48, v16
	v_and_b32_e32 v16, 32, v7
	s_waitcnt vmcnt(6)
	v_mov_b32_e32 v3, s8
	v_bitop3_b32 v7, v18, v16, v17 bitop3:0x36
	v_or_b32_e32 v17, v18, v17
	v_add_u32_e32 v3, s2, v3
	v_bitop3_b32 v16, s46, v17, v16 bitop3:0xf6
	s_ashr_i32 s57, s45, 31
	v_readfirstlane_b32 s61, v3
	s_add_i32 s58, s12, 0
	s_lshl_b32 s8, s13, 1
	s_barrier
	s_branch .LBB0_1813

; #define PG8_STAGE(bufoff, gbase, voff) do { _Pragma("unroll") for (int _i = 0; _i < 2; ++_i) \
;         __builtin_amdgcn_global_load_lds((const unsigned*)((const char*)(gbase) + (voff)[_i]), (LAS unsigned*)(lds + (bufoff) + ldsw + _i * 8192), 16, 0, 0); } while (0)
; #define PG8_WAIT_V(n) asm volatile("s_waitcnt vmcnt(" #n ")" ::: "memory")
; #define PG8_BAR __builtin_amdgcn_s_barrier()
; template <class Epi, class Sched, bool ALIGN_EPI>
; __device__ __forceinline__ void gemm_phase(LAS unsigned char* lds, const bf16_t* Ab, const bf16_t* Bb, int lda, int ldb, int K, const Sched& S, Epi& E) {
;     ...
;     const char* cA = (const char*)(Ab + cur.a_off); const char* cB = (const char*)(Bb + cur.b_off);
;     PG8_STAGE(PG8_SB(0, 0), cB, voffB); PG8_STAGE(PG8_SB(0, 1), cB + hstepB, voffB); PG8_STAGE(PG8_SA(0, 0), cA, voffA); PG8_STAGE(PG8_SA(0, 1), cA + hstepA, voffA);
;     if (wr == 1) PG8_BAR;
;     PG8_WAIT_V(2); PG8_BAR;
;     PG8_STAGE(PG8_SB(1, 0), cB + kstep, voffB); PG8_STAGE(PG8_SA(1, 0), cA + kstep, voffA); PG8_STAGE(PG8_SB(1, 1), cB + hstepB + kstep, voffB);
;     PG8_WAIT_V(6); PG8_BAR;
; __global__ void __launch_bounds__(512, 2) fwd_kernel(Args a) {
;     ...
;         for (int rep = (PROBE == 7 ? 0 : 1); rep < 2; ++rep)
;         { PH StdSched S; S.init(T, D, G, bid, D, D); EpiResid E{hb, ssb + (size_t)(4 * l + 3) * T * 16, (PROBE == 7 && rep == 0) ? 0.f : 1.f, nullptr, nullptr};
;           gemm_phase<EpiResid, StdSched, true>(lds, (const bf16_t*)(ar + AR_OX), (const bf16_t*)(wl + W_O), D, D, D, S, E); }
.LBB0_1879:
	s_andn2_b64 vcc, exec, s[12:13]
	s_cbranch_vccnz .LBB0_1915
	v_bfe_i32 v3, v10, 27, 1
	v_lshlrev_b32_e32 v2, 4, v10
	v_lshrrev_b32_e32 v3, 22, v3
	v_add_u32_e32 v3, v2, v3
	v_and_b32_e32 v3, 0xfffffc00, v3
	v_sub_u32_e32 v3, v2, v3
	v_ashrrev_i32_e32 v0, 31, v10
	v_lshrrev_b32_e32 v4, 4, v3
	v_lshrrev_b32_e32 v0, 26, v0
	v_bitop3_b32 v3, v4, v3, 32 bitop3:0x6c
	v_add_u32_e32 v0, v10, v0
	v_ashrrev_i32_e32 v5, 31, v3
	v_ashrrev_i32_e32 v0, 6, v0
	v_lshrrev_b32_e32 v5, 26, v5
	v_lshlrev_b32_e32 v4, 3, v0
	v_add_u32_e32 v5, v3, v5
	v_and_b32_e32 v4, -16, v4
	v_ashrrev_i32_e32 v6, 6, v5
	v_and_b32_e32 v5, 0xc0, v5
	v_add_u32_e32 v4, v6, v4
	v_sub_u32_e32 v3, v3, v5
	v_lshlrev_b32_e32 v0, 5, v0
	v_ashrrev_i16_sdwa v3, v254, sext(v3) dst_sel:DWORD dst_unused:UNUSED_PAD src0_sel:DWORD src1_sel:BYTE_0
	v_lshlrev_b32_e32 v5, 1, v4
	v_lshrrev_b32_e32 v7, 2, v4
	v_and_b32_e32 v6, 3, v6
	v_and_b32_e32 v0, 32, v0
	v_bfe_i32 v3, v3, 0, 16
	v_and_b32_e32 v5, 24, v5
	v_and_b32_e32 v7, 4, v7
	v_and_or_b32 v6, v4, s86, v6
	v_or3_b32 v5, v6, v7, v5
	v_add_lshl_u32 v3, v0, v3, 1
	v_add_u32_e32 v2, 0x2000, v2
	v_lshl_add_u32 v0, v4, 11, v3
	v_lshl_add_u32 v130, v5, 11, v3
	v_ashrrev_i32_e32 v3, 31, v2
	v_lshrrev_b32_e32 v3, 22, v3
	v_add_u32_e32 v3, v2, v3
	v_ashrrev_i32_e32 v3, 10, v3
	v_readlane_b32 s4, v255, 12
	v_mul_i32_i24_e32 v4, 0x400, v3
	s_waitcnt lgkmcnt(0)
	s_add_u32 s12, s6, s4
	v_sub_u32_e32 v2, v2, v4
	s_addc_u32 s13, s7, 0
	v_lshrrev_b32_e32 v4, 4, v2
	s_load_dwordx2 s[4:5], s[0:1], 0x120
	s_waitcnt lgkmcnt(0)
	v_bitop3_b32 v2, v4, v2, 32 bitop3:0x6c
	v_ashrrev_i32_e32 v5, 31, v2
	s_add_u32 s21, s12, 0x3e00000
	v_lshrrev_b32_e32 v5, 26, v5
	s_addc_u32 s22, s13, 0
	s_ashr_i32 s15, s14, 6
	v_lshlrev_b32_e32 v4, 3, v3
	v_add_u32_e32 v5, v2, v5
	v_and_b32_e32 v4, -16, v4
	v_ashrrev_i32_e32 v6, 6, v5
	v_and_b32_e32 v5, 0xc0, v5
	s_ashr_i32 s17, s14, 8
	s_lshl_b32 s24, s15, 10
	s_lshl_b64 s[10:11], s[10:11], 1
	v_add_u32_e32 v4, v6, v4
	v_sub_u32_e32 v2, v2, v5
	s_add_u32 s54, s21, s10
	v_lshlrev_b32_e32 v3, 5, v3
	v_ashrrev_i16_sdwa v2, v254, sext(v2) dst_sel:DWORD dst_unused:UNUSED_PAD src0_sel:DWORD src1_sel:BYTE_0
	v_lshlrev_b32_e32 v5, 1, v4
	v_lshrrev_b32_e32 v7, 2, v4
	v_and_b32_e32 v6, 3, v6
	s_addc_u32 s55, s22, s11
	s_add_i32 s33, s24, 0
	v_and_b32_e32 v3, 32, v3
	v_bfe_i32 v2, v2, 0, 16
	v_and_b32_e32 v5, 24, v5
	v_and_b32_e32 v7, 4, v7
	v_and_or_b32 v6, v4, s86, v6
	s_add_i32 m0, s33, 0x10000
	v_or3_b32 v5, v6, v7, v5
	v_add_lshl_u32 v2, v3, v2, 1
	global_load_lds_dwordx4 v130, s[54:55]
	s_add_i32 m0, s33, 0x12000
	v_lshl_add_u32 v132, v5, 11, v2
	s_add_u32 s10, s54, 0x40000
	global_load_lds_dwordx4 v132, s[54:55]
	s_addc_u32 s11, s55, 0
	s_add_i32 m0, s33, 0x14000
	s_lshl_b64 s[8:9], s[8:9], 1
	global_load_lds_dwordx4 v130, s[10:11]
	s_add_i32 m0, s33, 0x16000
	s_add_u32 s56, s4, s8
	s_addc_u32 s57, s5, s9
	s_add_i32 s31, s33, 0x2000
	global_load_lds_dwordx4 v132, s[10:11]
	s_mov_b32 m0, s33
	s_add_u32 s8, s56, 0x40000
	v_lshl_add_u32 v134, v4, 11, v2
	global_load_lds_dwordx4 v0, s[56:57]
	s_mov_b32 m0, s31
	s_addc_u32 s9, s57, 0
	s_add_i32 s39, s33, 0x4000
	global_load_lds_dwordx4 v134, s[56:57]
	s_mov_b32 m0, s39
	s_add_i32 s44, s33, 0x6000
	global_load_lds_dwordx4 v0, s[8:9]
	s_mov_b32 m0, s44
	v_mov_b32_e32 v131, v1
	global_load_lds_dwordx4 v134, s[8:9]
	v_mov_b32_e32 v133, v1
	v_mov_b32_e32 v135, v1
	s_cmp_eq_u32 s17, 1
	v_lshl_add_u64 v[8:9], s[54:55], 0, v[130:131]
	v_lshl_add_u64 v[6:7], s[54:55], 0, v[132:133]
	v_lshl_add_u64 v[2:3], s[56:57], 0, v[0:1]
	s_cselect_b64 s[8:9], -1, 0
	s_cmp_lg_u32 s17, 1
	v_lshl_add_u64 v[4:5], s[56:57], 0, v[134:135]
	s_cbranch_scc1 .LBB0_1882
	s_barrier
